# GLU epilogue: store-only waits between row groups dropped (all gate loads already landed)
# baseline (speedup 1.0000x reference)
.LBB0_616:
	v_lshl_add_u32 v146, s20, 8, v148
	v_lshl_or_b32 v144, s21, 7, v150
	v_ashrrev_i32_e32 v147, 31, v146
	v_ashrrev_i32_e32 v145, 31, v144
	v_lshlrev_b64 v[154:155], 13, v[146:147]
	v_lshl_add_u64 v[154:155], s[8:9], 0, v[154:155]
	v_lshlrev_b64 v[144:145], 1, v[144:145]
	v_lshl_add_u64 v[154:155], v[154:155], 0, v[144:145]
	v_add_co_u32_e32 v216, vcc, 0x20000, v154
	v_addc_co_u32_e32 v217, vcc, 0, v155, vcc
	global_load_dwordx4 v[220:223], v[216:217], off
	v_add_co_u32_e32 v216, vcc, 0x40000, v154
	v_addc_co_u32_e32 v217, vcc, 0, v155, vcc
	global_load_dwordx4 v[224:227], v[216:217], off
	v_add_co_u32_e32 v216, vcc, 0x60000, v154
	v_addc_co_u32_e32 v217, vcc, 0, v155, vcc
	global_load_dwordx4 v[228:231], v[216:217], off
	v_add_co_u32_e32 v216, vcc, 0x100000, v154
	v_addc_co_u32_e32 v217, vcc, 0, v155, vcc
	global_load_dwordx4 v[232:235], v[216:217], off
	v_add_co_u32_e32 v216, vcc, 0x120000, v154
	v_addc_co_u32_e32 v217, vcc, 0, v155, vcc
	global_load_dwordx4 v[236:239], v[216:217], off
	v_add_co_u32_e32 v216, vcc, 0x140000, v154
	v_addc_co_u32_e32 v217, vcc, 0, v155, vcc
	global_load_dwordx4 v[240:243], v[216:217], off
	v_add_co_u32_e32 v216, vcc, 0x160000, v154
	v_addc_co_u32_e32 v217, vcc, 0, v155, vcc
	global_load_dwordx4 v[244:247], v[216:217], off
	global_load_dwordx4 v[154:157], v[154:155], off
	v_mul_f32_e32 v116, 0xbfb8aa3b, v116
	v_mul_f32_e32 v117, 0xbfb8aa3b, v117
	v_exp_f32_e32 v116, v116
	v_exp_f32_e32 v117, v117
	v_mul_f32_e32 v112, 0xbfb8aa3b, v112
	v_mul_f32_e32 v113, 0xbfb8aa3b, v113
	v_mul_f32_e32 v114, 0xbfb8aa3b, v114
	v_mul_f32_e32 v115, 0xbfb8aa3b, v115
	v_mul_f32_e32 v118, 0xbfb8aa3b, v118
	v_mul_f32_e32 v119, 0xbfb8aa3b, v119
	v_exp_f32_e32 v112, v112
	v_exp_f32_e32 v113, v113
	v_exp_f32_e32 v114, v114
	v_exp_f32_e32 v115, v115
	v_exp_f32_e32 v118, v118
	v_exp_f32_e32 v119, v119
	v_add_f32_e32 v116, 1.0, v116
	v_add_f32_e32 v117, 1.0, v117
	v_rcp_f32_e32 v116, v116
	v_rcp_f32_e32 v117, v117
	v_add_f32_e32 v112, 1.0, v112
	v_add_f32_e32 v113, 1.0, v113
	v_add_f32_e32 v114, 1.0, v114
	v_add_f32_e32 v115, 1.0, v115
	v_add_f32_e32 v118, 1.0, v118
	v_add_f32_e32 v119, 1.0, v119
	v_rcp_f32_e32 v112, v112
	v_rcp_f32_e32 v113, v113
	v_rcp_f32_e32 v114, v114
	v_rcp_f32_e32 v115, v115
	v_rcp_f32_e32 v118, v118
	v_rcp_f32_e32 v119, v119
	v_mul_f32_e32 v100, 0xbfb8aa3b, v100
	v_mul_f32_e32 v101, 0xbfb8aa3b, v101
	v_exp_f32_e32 v100, v100
	v_exp_f32_e32 v101, v101
	v_mul_f32_e32 v96, 0xbfb8aa3b, v96
	v_mul_f32_e32 v97, 0xbfb8aa3b, v97
	v_mul_f32_e32 v98, 0xbfb8aa3b, v98
	v_mul_f32_e32 v99, 0xbfb8aa3b, v99
	v_mul_f32_e32 v102, 0xbfb8aa3b, v102
	v_mul_f32_e32 v103, 0xbfb8aa3b, v103
	v_exp_f32_e32 v96, v96
	v_exp_f32_e32 v97, v97
	v_exp_f32_e32 v98, v98
	v_exp_f32_e32 v99, v99
	v_exp_f32_e32 v102, v102
	v_exp_f32_e32 v103, v103
	v_add_f32_e32 v100, 1.0, v100
	v_add_f32_e32 v101, 1.0, v101
	v_rcp_f32_e32 v100, v100
	v_rcp_f32_e32 v101, v101
	v_add_f32_e32 v96, 1.0, v96
	v_add_f32_e32 v97, 1.0, v97
	v_add_f32_e32 v98, 1.0, v98
	v_add_f32_e32 v99, 1.0, v99
	v_add_f32_e32 v102, 1.0, v102
	v_add_f32_e32 v103, 1.0, v103
	v_rcp_f32_e32 v96, v96
	v_rcp_f32_e32 v97, v97
	v_rcp_f32_e32 v98, v98
	v_rcp_f32_e32 v99, v99
	v_rcp_f32_e32 v102, v102
	v_rcp_f32_e32 v103, v103
	v_mul_f32_e32 v84, 0xbfb8aa3b, v84
	v_mul_f32_e32 v85, 0xbfb8aa3b, v85
	v_exp_f32_e32 v84, v84
	v_exp_f32_e32 v85, v85
	v_mul_f32_e32 v80, 0xbfb8aa3b, v80
	v_mul_f32_e32 v81, 0xbfb8aa3b, v81
	v_mul_f32_e32 v82, 0xbfb8aa3b, v82
	v_mul_f32_e32 v83, 0xbfb8aa3b, v83
	v_mul_f32_e32 v86, 0xbfb8aa3b, v86
	v_mul_f32_e32 v87, 0xbfb8aa3b, v87
	v_exp_f32_e32 v80, v80
	v_exp_f32_e32 v81, v81
	v_exp_f32_e32 v82, v82
	v_exp_f32_e32 v83, v83
	v_exp_f32_e32 v86, v86
	s_waitcnt vmcnt(0)
	v_lshlrev_b32_e32 v158, 16, v154
	v_and_b32_e32 v159, 0xffff0000, v154
	v_lshlrev_b32_e32 v160, 16, v156
	v_and_b32_e32 v161, 0xffff0000, v156
	v_lshlrev_b32_e32 v156, 16, v157
	v_and_b32_e32 v157, 0xffff0000, v157
	v_pk_mul_f32 v[124:125], v[124:125], v[158:159]
	v_lshlrev_b32_e32 v154, 16, v155
	v_and_b32_e32 v155, 0xffff0000, v155
	v_pk_mul_f32 v[116:117], v[116:117], v[124:125]
	v_pk_mul_f32 v[120:121], v[120:121], v[160:161]
	v_pk_mul_f32 v[122:123], v[122:123], v[156:157]
	v_pk_mul_f32 v[126:127], v[126:127], v[154:155]
	v_pk_mul_f32 v[122:123], v[114:115], v[122:123]
	v_pk_mul_f32 v[114:115], v[112:113], v[120:121]
	v_cvt_pk_bf16_f32 v112, v116, v117
	v_lshlrev_b64 v[116:117], 12, v[146:147]
	v_pk_mul_f32 v[118:119], v[118:119], v[126:127]
	v_lshl_add_u64 v[116:117], s[96:97], 0, v[116:117]
	v_cvt_pk_bf16_f32 v113, v118, v119
	v_cvt_pk_bf16_f32 v114, v114, v115
	v_cvt_pk_bf16_f32 v115, v122, v123
	v_lshl_add_u64 v[116:117], v[116:117], 0, v[144:145]
	global_store_dwordx4 v[116:117], v[112:115], off
	v_exp_f32_e32 v87, v87
	v_add_f32_e32 v84, 1.0, v84
	v_or_b32_e32 v112, 16, v146
	v_ashrrev_i32_e32 v113, 31, v112
	v_lshlrev_b64 v[114:115], 13, v[112:113]
	v_lshl_add_u64 v[114:115], s[8:9], 0, v[114:115]
	v_lshl_add_u64 v[114:115], v[114:115], 0, v[144:145]
	v_mov_b32_e32 v114, v220
	v_mov_b32_e32 v115, v221
	v_mov_b32_e32 v116, v222
	v_mov_b32_e32 v117, v223
	v_add_f32_e32 v85, 1.0, v85
	v_rcp_f32_e32 v84, v84
	v_rcp_f32_e32 v85, v85
	v_add_f32_e32 v80, 1.0, v80
	v_add_f32_e32 v81, 1.0, v81
	v_add_f32_e32 v82, 1.0, v82
	v_add_f32_e32 v83, 1.0, v83
	v_add_f32_e32 v86, 1.0, v86
	v_add_f32_e32 v87, 1.0, v87
	v_rcp_f32_e32 v80, v80
	v_rcp_f32_e32 v81, v81
	v_rcp_f32_e32 v82, v82
	v_rcp_f32_e32 v83, v83
	v_rcp_f32_e32 v86, v86
	v_rcp_f32_e32 v87, v87
	v_mul_f32_e32 v68, 0xbfb8aa3b, v68
	v_mul_f32_e32 v69, 0xbfb8aa3b, v69
	v_exp_f32_e32 v68, v68
	v_exp_f32_e32 v69, v69
	v_mul_f32_e32 v64, 0xbfb8aa3b, v64
	v_mul_f32_e32 v65, 0xbfb8aa3b, v65
	v_mul_f32_e32 v66, 0xbfb8aa3b, v66
	v_mul_f32_e32 v67, 0xbfb8aa3b, v67
	v_mul_f32_e32 v70, 0xbfb8aa3b, v70
	v_mul_f32_e32 v71, 0xbfb8aa3b, v71
	v_exp_f32_e32 v64, v64
	v_exp_f32_e32 v65, v65
	v_exp_f32_e32 v66, v66
	v_exp_f32_e32 v67, v67
	v_exp_f32_e32 v70, v70
	v_exp_f32_e32 v71, v71
	v_add_f32_e32 v68, 1.0, v68
	v_add_f32_e32 v69, 1.0, v69
	v_rcp_f32_e32 v68, v68
	v_rcp_f32_e32 v69, v69
	v_add_f32_e32 v64, 1.0, v64
	v_add_f32_e32 v65, 1.0, v65
	v_add_f32_e32 v66, 1.0, v66
	v_add_f32_e32 v67, 1.0, v67
	v_add_f32_e32 v70, 1.0, v70
	v_add_f32_e32 v71, 1.0, v71
	v_rcp_f32_e32 v64, v64
	v_rcp_f32_e32 v65, v65
	v_rcp_f32_e32 v66, v66
	v_rcp_f32_e32 v67, v67
	v_rcp_f32_e32 v70, v70
	v_rcp_f32_e32 v71, v71
	v_mul_f32_e32 v52, 0xbfb8aa3b, v52
	v_mul_f32_e32 v53, 0xbfb8aa3b, v53
	v_exp_f32_e32 v52, v52
	v_exp_f32_e32 v53, v53
	v_mul_f32_e32 v48, 0xbfb8aa3b, v48
	v_mul_f32_e32 v49, 0xbfb8aa3b, v49
	v_mul_f32_e32 v50, 0xbfb8aa3b, v50
	v_mul_f32_e32 v51, 0xbfb8aa3b, v51
	v_mul_f32_e32 v54, 0xbfb8aa3b, v54
	v_mul_f32_e32 v55, 0xbfb8aa3b, v55
	v_exp_f32_e32 v48, v48
	v_exp_f32_e32 v49, v49
	v_exp_f32_e32 v50, v50
	v_exp_f32_e32 v51, v51
	v_exp_f32_e32 v54, v54
	v_exp_f32_e32 v55, v55
	v_add_f32_e32 v52, 1.0, v52
	v_add_f32_e32 v53, 1.0, v53
	v_rcp_f32_e32 v52, v52
	v_rcp_f32_e32 v53, v53
	v_add_f32_e32 v48, 1.0, v48
	v_add_f32_e32 v49, 1.0, v49
	v_add_f32_e32 v50, 1.0, v50
	v_add_f32_e32 v51, 1.0, v51
	v_add_f32_e32 v54, 1.0, v54
	v_add_f32_e32 v55, 1.0, v55
	v_rcp_f32_e32 v48, v48
	v_rcp_f32_e32 v49, v49
	v_rcp_f32_e32 v50, v50
	v_rcp_f32_e32 v51, v51
	v_rcp_f32_e32 v54, v54
	v_rcp_f32_e32 v55, v55
	s_nop 0
	v_lshlrev_b32_e32 v118, 16, v114
	v_and_b32_e32 v119, 0xffff0000, v114
	v_lshlrev_b32_e32 v120, 16, v116
	v_and_b32_e32 v121, 0xffff0000, v116
	v_lshlrev_b32_e32 v116, 16, v117
	v_and_b32_e32 v117, 0xffff0000, v117
	v_pk_mul_f32 v[108:109], v[108:109], v[118:119]
	v_lshlrev_b32_e32 v114, 16, v115
	v_and_b32_e32 v115, 0xffff0000, v115
	v_pk_mul_f32 v[100:101], v[100:101], v[108:109]
	v_pk_mul_f32 v[104:105], v[104:105], v[120:121]
	v_pk_mul_f32 v[106:107], v[106:107], v[116:117]
	v_pk_mul_f32 v[110:111], v[110:111], v[114:115]
	v_pk_mul_f32 v[106:107], v[98:99], v[106:107]
	v_pk_mul_f32 v[98:99], v[96:97], v[104:105]
	v_cvt_pk_bf16_f32 v96, v100, v101
	v_lshlrev_b64 v[100:101], 12, v[112:113]
	v_pk_mul_f32 v[102:103], v[102:103], v[110:111]
	v_lshl_add_u64 v[100:101], s[96:97], 0, v[100:101]
	v_cvt_pk_bf16_f32 v97, v102, v103
	v_cvt_pk_bf16_f32 v98, v98, v99
	v_cvt_pk_bf16_f32 v99, v106, v107
	v_lshl_add_u64 v[100:101], v[100:101], 0, v[144:145]
	global_store_dwordx4 v[100:101], v[96:99], off
	v_mul_f32_e32 v36, 0xbfb8aa3b, v36
	v_mul_f32_e32 v37, 0xbfb8aa3b, v37
	v_or_b32_e32 v96, 32, v146
	v_ashrrev_i32_e32 v97, 31, v96
	v_lshlrev_b64 v[98:99], 13, v[96:97]
	v_lshl_add_u64 v[98:99], s[8:9], 0, v[98:99]
	v_lshl_add_u64 v[98:99], v[98:99], 0, v[144:145]
	v_mov_b32_e32 v98, v224
	v_mov_b32_e32 v99, v225
	v_mov_b32_e32 v100, v226
	v_mov_b32_e32 v101, v227
	v_exp_f32_e32 v36, v36
	v_exp_f32_e32 v37, v37
	v_mul_f32_e32 v32, 0xbfb8aa3b, v32
	v_mul_f32_e32 v33, 0xbfb8aa3b, v33
	v_mul_f32_e32 v34, 0xbfb8aa3b, v34
	v_mul_f32_e32 v35, 0xbfb8aa3b, v35
	v_mul_f32_e32 v38, 0xbfb8aa3b, v38
	v_mul_f32_e32 v39, 0xbfb8aa3b, v39
	v_exp_f32_e32 v32, v32
	v_exp_f32_e32 v33, v33
	v_exp_f32_e32 v34, v34
	v_exp_f32_e32 v35, v35
	v_exp_f32_e32 v38, v38
	v_exp_f32_e32 v39, v39
	v_add_f32_e32 v36, 1.0, v36
	v_add_f32_e32 v37, 1.0, v37
	v_rcp_f32_e32 v36, v36
	v_rcp_f32_e32 v37, v37
	v_add_f32_e32 v32, 1.0, v32
	v_add_f32_e32 v33, 1.0, v33
	v_add_f32_e32 v34, 1.0, v34
	v_add_f32_e32 v35, 1.0, v35
	v_add_f32_e32 v38, 1.0, v38
	v_add_f32_e32 v39, 1.0, v39
	v_rcp_f32_e32 v32, v32
	v_rcp_f32_e32 v33, v33
	v_rcp_f32_e32 v34, v34
	v_rcp_f32_e32 v35, v35
	v_rcp_f32_e32 v38, v38
	v_rcp_f32_e32 v39, v39
	v_mul_f32_e32 v20, 0xbfb8aa3b, v20
	v_mul_f32_e32 v21, 0xbfb8aa3b, v21
	v_exp_f32_e32 v20, v20
	v_exp_f32_e32 v21, v21
	v_mul_f32_e32 v16, 0xbfb8aa3b, v16
	v_mul_f32_e32 v17, 0xbfb8aa3b, v17
	v_mul_f32_e32 v18, 0xbfb8aa3b, v18
	v_mul_f32_e32 v19, 0xbfb8aa3b, v19
	v_mul_f32_e32 v22, 0xbfb8aa3b, v22
	v_mul_f32_e32 v23, 0xbfb8aa3b, v23
	v_exp_f32_e32 v16, v16
	v_exp_f32_e32 v17, v17
	v_exp_f32_e32 v18, v18
	v_exp_f32_e32 v19, v19
	v_exp_f32_e32 v22, v22
	v_exp_f32_e32 v23, v23
	v_add_f32_e32 v20, 1.0, v20
	v_add_f32_e32 v21, 1.0, v21
	v_rcp_f32_e32 v20, v20
	v_rcp_f32_e32 v21, v21
	v_add_f32_e32 v16, 1.0, v16
	v_add_f32_e32 v17, 1.0, v17
	v_add_f32_e32 v18, 1.0, v18
	v_add_f32_e32 v19, 1.0, v19
	v_add_f32_e32 v22, 1.0, v22
	v_add_f32_e32 v23, 1.0, v23
	v_rcp_f32_e32 v16, v16
	v_rcp_f32_e32 v17, v17
	v_rcp_f32_e32 v18, v18
	v_rcp_f32_e32 v19, v19
	v_rcp_f32_e32 v22, v22
	v_rcp_f32_e32 v23, v23
	v_mul_f32_e32 v4, 0xbfb8aa3b, v4
	v_mul_f32_e32 v5, 0xbfb8aa3b, v5
	v_exp_f32_e32 v4, v4
	v_exp_f32_e32 v5, v5
	v_mul_f32_e32 v0, 0xbfb8aa3b, v0
	v_mul_f32_e32 v1, 0xbfb8aa3b, v1
	v_mul_f32_e32 v2, 0xbfb8aa3b, v2
	v_mul_f32_e32 v3, 0xbfb8aa3b, v3
	v_mul_f32_e32 v6, 0xbfb8aa3b, v6
	v_mul_f32_e32 v7, 0xbfb8aa3b, v7
	v_exp_f32_e32 v0, v0
	v_exp_f32_e32 v1, v1
	v_exp_f32_e32 v2, v2
	v_exp_f32_e32 v3, v3
	v_exp_f32_e32 v6, v6
	v_exp_f32_e32 v7, v7
	v_add_f32_e32 v4, 1.0, v4
	s_nop 0
	v_lshlrev_b32_e32 v102, 16, v98
	v_and_b32_e32 v103, 0xffff0000, v98
	v_lshlrev_b32_e32 v104, 16, v100
	v_and_b32_e32 v105, 0xffff0000, v100
	v_lshlrev_b32_e32 v100, 16, v101
	v_and_b32_e32 v101, 0xffff0000, v101
	v_pk_mul_f32 v[92:93], v[92:93], v[102:103]
	v_lshlrev_b32_e32 v98, 16, v99
	v_and_b32_e32 v99, 0xffff0000, v99
	v_pk_mul_f32 v[84:85], v[84:85], v[92:93]
	v_pk_mul_f32 v[88:89], v[88:89], v[104:105]
	v_pk_mul_f32 v[90:91], v[90:91], v[100:101]
	v_pk_mul_f32 v[94:95], v[94:95], v[98:99]
	v_pk_mul_f32 v[90:91], v[82:83], v[90:91]
	v_pk_mul_f32 v[82:83], v[80:81], v[88:89]
	v_cvt_pk_bf16_f32 v80, v84, v85
	v_lshlrev_b64 v[84:85], 12, v[96:97]
	v_pk_mul_f32 v[86:87], v[86:87], v[94:95]
	v_lshl_add_u64 v[84:85], s[96:97], 0, v[84:85]
	v_cvt_pk_bf16_f32 v81, v86, v87
	v_cvt_pk_bf16_f32 v82, v82, v83
	v_cvt_pk_bf16_f32 v83, v90, v91
	v_lshl_add_u64 v[84:85], v[84:85], 0, v[144:145]
	global_store_dwordx4 v[84:85], v[80:83], off
	v_add_f32_e32 v5, 1.0, v5
	v_rcp_f32_e32 v4, v4
	v_or_b32_e32 v80, 48, v146
	v_ashrrev_i32_e32 v81, 31, v80
	v_lshlrev_b64 v[82:83], 13, v[80:81]
	v_lshl_add_u64 v[82:83], s[8:9], 0, v[82:83]
	v_lshl_add_u64 v[82:83], v[82:83], 0, v[144:145]
	v_mov_b32_e32 v82, v228
	v_mov_b32_e32 v83, v229
	v_mov_b32_e32 v84, v230
	v_mov_b32_e32 v85, v231
	v_rcp_f32_e32 v5, v5
	v_add_f32_e32 v0, 1.0, v0
	v_add_f32_e32 v1, 1.0, v1
	v_add_f32_e32 v2, 1.0, v2
	v_add_f32_e32 v3, 1.0, v3
	v_add_f32_e32 v6, 1.0, v6
	v_add_f32_e32 v7, 1.0, v7
	v_rcp_f32_e32 v0, v0
	v_rcp_f32_e32 v1, v1
	v_rcp_f32_e32 v2, v2
	v_rcp_f32_e32 v3, v3
	v_rcp_f32_e32 v6, v6
	v_rcp_f32_e32 v7, v7
	s_mov_b64 s[20:21], -1
	s_andn2_b64 vcc, exec, s[38:39]
	s_nop 0
	v_lshlrev_b32_e32 v86, 16, v82
	v_and_b32_e32 v87, 0xffff0000, v82
	v_lshlrev_b32_e32 v88, 16, v84
	v_and_b32_e32 v89, 0xffff0000, v84
	v_lshlrev_b32_e32 v84, 16, v85
	v_and_b32_e32 v85, 0xffff0000, v85
	v_pk_mul_f32 v[76:77], v[76:77], v[86:87]
	v_lshlrev_b32_e32 v82, 16, v83
	v_and_b32_e32 v83, 0xffff0000, v83
	v_pk_mul_f32 v[68:69], v[68:69], v[76:77]
	v_pk_mul_f32 v[72:73], v[72:73], v[88:89]
	v_pk_mul_f32 v[74:75], v[74:75], v[84:85]
	v_pk_mul_f32 v[78:79], v[78:79], v[82:83]
	v_pk_mul_f32 v[74:75], v[66:67], v[74:75]
	v_pk_mul_f32 v[66:67], v[64:65], v[72:73]
	v_cvt_pk_bf16_f32 v64, v68, v69
	v_lshlrev_b64 v[68:69], 12, v[80:81]
	v_pk_mul_f32 v[70:71], v[70:71], v[78:79]
	v_lshl_add_u64 v[68:69], s[96:97], 0, v[68:69]
	v_cvt_pk_bf16_f32 v65, v70, v71
	v_cvt_pk_bf16_f32 v66, v66, v67
	v_cvt_pk_bf16_f32 v67, v74, v75
	v_lshl_add_u64 v[68:69], v[68:69], 0, v[144:145]
	global_store_dwordx4 v[68:69], v[64:67], off
	s_nop 1
	v_add_u32_e32 v64, 0x80, v146
	v_ashrrev_i32_e32 v65, 31, v64
	v_lshlrev_b64 v[66:67], 13, v[64:65]
	v_lshl_add_u64 v[66:67], s[8:9], 0, v[66:67]
	v_lshl_add_u64 v[66:67], v[66:67], 0, v[144:145]
	v_mov_b32_e32 v66, v232
	v_mov_b32_e32 v67, v233
	v_mov_b32_e32 v68, v234
	v_mov_b32_e32 v69, v235
	s_nop 0
	v_lshlrev_b32_e32 v70, 16, v66
	v_and_b32_e32 v71, 0xffff0000, v66
	v_lshlrev_b32_e32 v72, 16, v68
	v_and_b32_e32 v73, 0xffff0000, v68
	v_lshlrev_b32_e32 v68, 16, v69
	v_and_b32_e32 v69, 0xffff0000, v69
	v_pk_mul_f32 v[60:61], v[60:61], v[70:71]
	v_lshlrev_b32_e32 v66, 16, v67
	v_and_b32_e32 v67, 0xffff0000, v67
	v_pk_mul_f32 v[52:53], v[52:53], v[60:61]
	v_pk_mul_f32 v[56:57], v[56:57], v[72:73]
	v_pk_mul_f32 v[58:59], v[58:59], v[68:69]
	v_pk_mul_f32 v[62:63], v[62:63], v[66:67]
	v_pk_mul_f32 v[58:59], v[50:51], v[58:59]
	v_pk_mul_f32 v[50:51], v[48:49], v[56:57]
	v_cvt_pk_bf16_f32 v48, v52, v53
	v_lshlrev_b64 v[52:53], 12, v[64:65]
	v_pk_mul_f32 v[54:55], v[54:55], v[62:63]
	v_lshl_add_u64 v[52:53], s[96:97], 0, v[52:53]
	v_cvt_pk_bf16_f32 v49, v54, v55
	v_cvt_pk_bf16_f32 v50, v50, v51
	v_cvt_pk_bf16_f32 v51, v58, v59
	v_lshl_add_u64 v[52:53], v[52:53], 0, v[144:145]
	global_store_dwordx4 v[52:53], v[48:51], off
	s_nop 1
	v_add_u32_e32 v48, 0x90, v146
	v_ashrrev_i32_e32 v49, 31, v48
	v_lshlrev_b64 v[50:51], 13, v[48:49]
	v_lshl_add_u64 v[50:51], s[8:9], 0, v[50:51]
	v_lshl_add_u64 v[50:51], v[50:51], 0, v[144:145]
	v_mov_b32_e32 v50, v236
	v_mov_b32_e32 v51, v237
	v_mov_b32_e32 v52, v238
	v_mov_b32_e32 v53, v239
	s_nop 0
	v_lshlrev_b32_e32 v54, 16, v50
	v_and_b32_e32 v55, 0xffff0000, v50
	v_lshlrev_b32_e32 v56, 16, v52
	v_and_b32_e32 v57, 0xffff0000, v52
	v_lshlrev_b32_e32 v52, 16, v53
	v_and_b32_e32 v53, 0xffff0000, v53
	v_pk_mul_f32 v[44:45], v[44:45], v[54:55]
	v_lshlrev_b32_e32 v50, 16, v51
	v_and_b32_e32 v51, 0xffff0000, v51
	v_pk_mul_f32 v[36:37], v[36:37], v[44:45]
	v_pk_mul_f32 v[40:41], v[40:41], v[56:57]
	v_pk_mul_f32 v[42:43], v[42:43], v[52:53]
	v_pk_mul_f32 v[46:47], v[46:47], v[50:51]
	v_pk_mul_f32 v[42:43], v[34:35], v[42:43]
	v_pk_mul_f32 v[34:35], v[32:33], v[40:41]
	v_cvt_pk_bf16_f32 v32, v36, v37
	v_lshlrev_b64 v[36:37], 12, v[48:49]
	v_pk_mul_f32 v[38:39], v[38:39], v[46:47]
	v_lshl_add_u64 v[36:37], s[96:97], 0, v[36:37]
	v_cvt_pk_bf16_f32 v33, v38, v39
	v_cvt_pk_bf16_f32 v34, v34, v35
	v_cvt_pk_bf16_f32 v35, v42, v43
	v_lshl_add_u64 v[36:37], v[36:37], 0, v[144:145]
	global_store_dwordx4 v[36:37], v[32:35], off
	s_nop 1
	v_add_u32_e32 v32, 0xa0, v146
	v_ashrrev_i32_e32 v33, 31, v32
	v_lshlrev_b64 v[34:35], 13, v[32:33]
	v_lshl_add_u64 v[34:35], s[8:9], 0, v[34:35]
	v_lshl_add_u64 v[34:35], v[34:35], 0, v[144:145]
	v_mov_b32_e32 v34, v240
	v_mov_b32_e32 v35, v241
	v_mov_b32_e32 v36, v242
	v_mov_b32_e32 v37, v243
	s_nop 0
	v_lshlrev_b32_e32 v38, 16, v34
	v_and_b32_e32 v39, 0xffff0000, v34
	v_lshlrev_b32_e32 v40, 16, v36
	v_and_b32_e32 v41, 0xffff0000, v36
	v_lshlrev_b32_e32 v36, 16, v37
	v_and_b32_e32 v37, 0xffff0000, v37
	v_pk_mul_f32 v[28:29], v[28:29], v[38:39]
	v_lshlrev_b32_e32 v34, 16, v35
	v_and_b32_e32 v35, 0xffff0000, v35
	v_pk_mul_f32 v[20:21], v[20:21], v[28:29]
	v_pk_mul_f32 v[24:25], v[24:25], v[40:41]
	v_pk_mul_f32 v[26:27], v[26:27], v[36:37]
	v_pk_mul_f32 v[30:31], v[30:31], v[34:35]
	v_pk_mul_f32 v[26:27], v[18:19], v[26:27]
	v_pk_mul_f32 v[18:19], v[16:17], v[24:25]
	v_cvt_pk_bf16_f32 v16, v20, v21
	v_lshlrev_b64 v[20:21], 12, v[32:33]
	v_pk_mul_f32 v[22:23], v[22:23], v[30:31]
	v_lshl_add_u64 v[20:21], s[96:97], 0, v[20:21]
	v_cvt_pk_bf16_f32 v17, v22, v23
	v_cvt_pk_bf16_f32 v18, v18, v19
	v_cvt_pk_bf16_f32 v19, v26, v27
	v_lshl_add_u64 v[20:21], v[20:21], 0, v[144:145]
	global_store_dwordx4 v[20:21], v[16:19], off
	s_nop 1
	v_add_u32_e32 v16, 0xb0, v146
	v_ashrrev_i32_e32 v17, 31, v16
	v_lshlrev_b64 v[18:19], 13, v[16:17]
	v_lshl_add_u64 v[18:19], s[8:9], 0, v[18:19]
	v_lshl_add_u64 v[18:19], v[18:19], 0, v[144:145]
	v_mov_b32_e32 v18, v244
	v_mov_b32_e32 v19, v245
	v_mov_b32_e32 v20, v246
	v_mov_b32_e32 v21, v247
	s_nop 0
	v_lshlrev_b32_e32 v22, 16, v18
	v_and_b32_e32 v23, 0xffff0000, v18
	v_lshlrev_b32_e32 v24, 16, v20
	v_and_b32_e32 v25, 0xffff0000, v20
	v_lshlrev_b32_e32 v20, 16, v21
	v_and_b32_e32 v21, 0xffff0000, v21
	v_pk_mul_f32 v[12:13], v[12:13], v[22:23]
	v_lshlrev_b32_e32 v18, 16, v19
	v_and_b32_e32 v19, 0xffff0000, v19
	v_pk_mul_f32 v[4:5], v[4:5], v[12:13]
	v_pk_mul_f32 v[8:9], v[8:9], v[24:25]
	v_pk_mul_f32 v[10:11], v[10:11], v[20:21]
	v_pk_mul_f32 v[14:15], v[14:15], v[18:19]
	v_pk_mul_f32 v[10:11], v[2:3], v[10:11]
	v_pk_mul_f32 v[2:3], v[0:1], v[8:9]
	v_cvt_pk_bf16_f32 v0, v4, v5
	v_lshlrev_b64 v[4:5], 12, v[16:17]
	v_pk_mul_f32 v[6:7], v[6:7], v[14:15]
	v_lshl_add_u64 v[4:5], s[96:97], 0, v[4:5]
	v_cvt_pk_bf16_f32 v1, v6, v7
	v_cvt_pk_bf16_f32 v2, v2, v3
	v_cvt_pk_bf16_f32 v3, v10, v11
	v_lshl_add_u64 v[4:5], v[4:5], 0, v[144:145]
	global_store_dwordx4 v[4:5], v[0:3], off
	s_cbranch_vccnz .LBB0_605
	s_andn2_b64 vcc, exec, s[0:1]
	s_cbranch_vccnz .LBB0_604
	s_barrier
	s_branch .LBB0_604
